# v083 + P2 complementary half-grid order: WGs with blockIdx bit 3 set run their pre-product GEMM tile first and the spatial-gating/pooling part second (others unchanged), with s24/s25/s37-s51 saved/res
# speedup vs baseline: 1.0001x; 1.0001x over previous
.LBB0_384:
	s_or_b64 exec, exec, s[4:5]
	s_add_u32 s66, s56, 0x12400000
	s_waitcnt lgkmcnt(0)
	v_cndmask_b32_e64 v0, 0, 1, s[84:85]
	s_addc_u32 s67, s57, 0
	v_cmp_ne_u32_e64 s[4:5], 1, v0
	s_andn2_b64 vcc, exec, s[84:85]
	s_barrier
	s_mov_b32 s32, 0
	s_cmpk_lg_i32 s58, 0x100
	s_cbranch_scc1 .Lp2_normal
	s_bitcmp1_b32 s2, 3
	s_cbranch_scc0 .Lp2_normal
	v_writelane_b32 v241, s24, 0
	v_writelane_b32 v241, s25, 1
	s_mov_b32 s32, 1
	s_branch .LBB0_401
.Lp2_normal:
	s_cbranch_vccnz .LBB0_401
.Lp2_A_entry:
	s_add_u32 s38, s56, 0x7780000
	s_addc_u32 s39, s57, 0
	s_cmpk_eq_i32 s58, 0x100
	s_cselect_b64 s[6:7], -1, 0
	v_cndmask_b32_e64 v0, 0, 1, s[6:7]
	s_mov_b32 s6, s87
	s_mov_b32 s7, s88
	s_mov_b32 s8, s89
	s_mov_b32 s9, s90
	v_readlane_b32 s80, v240, 0
	v_readlane_b32 s81, v240, 1
	v_readlane_b32 s89, v240, 9
	v_readlane_b32 s90, v240, 10
	s_mov_b32 s90, s9
	s_mov_b32 s89, s8
	s_mov_b64 s[8:9], s[80:81]
	v_readlane_b32 s87, v240, 7
	v_readlane_b32 s88, v240, 8
	s_add_u32 s36, s8, 64
	s_mov_b32 s88, s7
	s_mov_b32 s87, s6
	s_addc_u32 s37, s9, 0
	v_cmp_ne_u32_e64 s[6:7], 1, v0
	v_mov_b32_e32 v61, 0
	s_mov_b32 s22, 0x10500000
	s_mov_b32 s23, 0x10600000
	s_mov_b32 s48, 0x10700000
	s_mov_b64 s[40:41], 0x400000
	s_movk_i32 s49, 0x80
	v_mov_b32_e32 v112, 0x358637bd
	s_mov_b32 s50, 0xf800000
	v_mov_b32_e32 v113, 0x260
	s_mov_b32 s51, 0xfffffe3
	s_movk_i32 s60, 0x110
	s_mov_b64 s[42:43], 0x10400000
	s_mov_b32 s61, 0xc400000
	s_mov_b32 s62, 0x12400000
	s_mov_b64 s[44:45], 0x100
	v_mbcnt_hi_u32_b32 v114, -1, v175
	v_mov_b32_e32 v115, 0x800
	s_mov_b32 s63, s2
	v_readlane_b32 s82, v240, 2
	v_readlane_b32 s83, v240, 3
	v_readlane_b32 s84, v240, 4
	v_readlane_b32 s85, v240, 5
	v_readlane_b32 s86, v240, 6
	v_readlane_b32 s91, v240, 11
	v_readlane_b32 s92, v240, 12
	v_readlane_b32 s93, v240, 13
	v_readlane_b32 s94, v240, 14
	v_readlane_b32 s95, v240, 15
	s_branch .LBB0_387

.LBB0_401:
	s_cmp_eq_u32 s32, 2
	s_cbranch_scc1 .Lp2_restoreB
	v_mov_b32_e32 v9, v174
	s_cmpk_gt_i32 s2, 0x7f
	v_readfirstlane_b32 s6, v9
	s_cbranch_scc1 .LBB0_421
	v_lshlrev_b32_e32 v0, 4, v9
	v_add_u32_e32 v1, 0x2000, v0
	v_ashrrev_i32_e32 v2, 31, v1
	v_lshrrev_b32_e32 v2, 22, v2
	v_add_u32_e32 v2, v1, v2
	v_ashrrev_i32_e32 v8, 10, v2
	v_mul_i32_i24_e32 v2, 0x400, v8
	v_sub_u32_e32 v1, v1, v2
	v_lshrrev_b32_e32 v2, 4, v1
	v_bitop3_b32 v1, v2, v1, 32 bitop3:0x6c
	v_ashrrev_i32_e32 v2, 31, v1
	v_lshrrev_b32_e32 v2, 26, v2
	v_add_u32_e32 v2, v1, v2
	v_lshlrev_b32_e32 v3, 3, v8
	v_ashrrev_i32_e32 v10, 6, v2
	v_and_b32_e32 v3, -16, v3
	v_add_u32_e32 v3, v10, v3
	v_and_b32_e32 v4, 3, v10
	s_mov_b32 s8, 0xfffe0
	v_lshrrev_b32_e32 v5, 2, v3
	v_lshlrev_b32_e32 v6, 1, v3
	v_and_b32_e32 v2, 0xc0, v2
	v_and_or_b32 v4, v3, s8, v4
	v_and_b32_e32 v5, 4, v5
	v_and_b32_e32 v6, 24, v6
	v_sub_u32_e32 v1, v1, v2
	v_mov_b32_e32 v2, 1
	v_or3_b32 v4, v4, v5, v6
	v_lshlrev_b32_e32 v5, 5, v8
	v_ashrrev_i16_sdwa v1, v2, sext(v1) dst_sel:DWORD dst_unused:UNUSED_PAD src0_sel:DWORD src1_sel:BYTE_0
	v_and_b32_e32 v5, 32, v5
	v_bfe_i32 v11, v1, 0, 16
	v_add_lshl_u32 v1, v5, v11, 1
	v_lshl_add_u32 v128, v4, 12, v1
	v_lshl_add_u32 v130, v3, 12, v1
	v_bfe_i32 v1, v9, 27, 1
	v_lshrrev_b32_e32 v1, 22, v1
	v_add_u32_e32 v1, v0, v1
	v_and_b32_e32 v1, 0xfffffc00, v1
	v_sub_u32_e32 v0, v0, v1
	v_lshrrev_b32_e32 v1, 4, v0
	v_ashrrev_i32_e32 v3, 31, v9
	v_bitop3_b32 v0, v1, v0, 32 bitop3:0x6c
	v_lshrrev_b32_e32 v3, 26, v3
	v_ashrrev_i32_e32 v1, 31, v0
	v_add_u32_e32 v3, v9, v3
	v_lshrrev_b32_e32 v1, 26, v1
	v_ashrrev_i32_e32 v13, 6, v3
	v_add_u32_e32 v1, v0, v1
	v_lshlrev_b32_e32 v3, 3, v13
	v_ashrrev_i32_e32 v12, 6, v1
	v_and_b32_e32 v3, -16, v3
	v_add_u32_e32 v3, v12, v3
	v_and_b32_e32 v4, 3, v12
	v_and_or_b32 v4, v3, s8, v4
	s_ashr_i32 s8, s2, 3
	s_ashr_i32 s7, s6, 6
	s_and_b32 s9, s8, -4
	s_lshl_b32 s8, s8, 18
	s_ashr_i32 s24, s6, 8
	s_lshl_b32 s10, s7, 10
	s_or_b32 s80, s9, s90
	s_and_b32 s79, s2, 7
	s_and_b32 s9, s2, 0x8000
	s_and_b32 s8, s8, 0x3ff00000
	s_add_u32 s8, s11, s8
	s_addc_u32 s22, s1, 0
	s_lshl_b32 s23, s90, 10
	s_add_u32 s8, s8, s23
	s_addc_u32 s25, s22, 0
	s_lshl_b32 s22, s79, 20
	s_add_u32 s33, s73, s22
	s_addc_u32 s36, s74, 0
	s_add_u32 s22, s75, s22
	s_addc_u32 s37, s76, 0
	s_add_u32 s23, s22, s23
	s_addc_u32 s37, s37, 0
	s_add_i32 s22, s10, 0
	s_add_i32 m0, s22, 0x10000
	s_add_i32 s38, s22, 0x12000
	s_lshl_b32 s39, s80, 20
	v_lshrrev_b32_e32 v5, 2, v3
	v_lshlrev_b32_e32 v6, 1, v3
	v_and_b32_e32 v1, 0xc0, v1
	s_add_u32 s39, s34, s39
	v_and_b32_e32 v5, 4, v5
	v_and_b32_e32 v6, 24, v6
	v_sub_u32_e32 v0, v0, v1
	s_addc_u32 s40, s35, 0
	s_lshl_b32 s41, s79, 9
	v_or3_b32 v4, v4, v5, v6
	v_lshlrev_b32_e32 v5, 5, v13
	v_ashrrev_i16_sdwa v0, v2, sext(v0) dst_sel:DWORD dst_unused:UNUSED_PAD src0_sel:DWORD src1_sel:BYTE_0
	s_add_u32 s39, s39, s41
	v_and_b32_e32 v5, 32, v5
	v_bfe_i32 v14, v0, 0, 16
	s_addc_u32 s40, s40, 0
	v_add_lshl_u32 v0, v5, v14, 1
	s_cmp_eq_u32 s9, 0
	v_lshl_add_u32 v132, v4, 12, v0
	s_cselect_b32 s47, s37, s36
	s_cselect_b32 s46, s23, s33
	global_load_lds_dwordx4 v132, s[46:47]
	s_mov_b32 m0, s38
	s_cselect_b32 s44, s8, s39
	s_cselect_b32 s45, s25, s40
	s_add_u32 s8, s46, 0x80000
	global_load_lds_dwordx4 v128, s[46:47]
	s_addc_u32 s9, s47, 0
	s_add_i32 m0, s22, 0x14000
	s_add_i32 s23, s22, 0x2000
	global_load_lds_dwordx4 v132, s[8:9]
	s_add_i32 m0, s22, 0x16000
	v_lshl_add_u32 v134, v3, 12, v0
	global_load_lds_dwordx4 v128, s[8:9]
	s_mov_b32 m0, s22
	s_add_u32 s8, s44, 0x80000
	global_load_lds_dwordx4 v134, s[44:45]
	s_mov_b32 m0, s23
	s_addc_u32 s9, s45, 0
	s_add_i32 s33, s22, 0x4000
	global_load_lds_dwordx4 v130, s[44:45]
	s_mov_b32 m0, s33
	s_add_i32 s50, s22, 0x6000
	global_load_lds_dwordx4 v134, s[8:9]
	s_mov_b32 m0, s50
	v_mov_b32_e32 v133, 0
	global_load_lds_dwordx4 v130, s[8:9]
	v_mov_b32_e32 v129, v133
	v_mov_b32_e32 v135, v133
	v_mov_b32_e32 v131, v133
	s_cmp_eq_u32 s24, 1
	s_mov_b32 s51, 0
	v_lshl_add_u64 v[6:7], s[46:47], 0, v[132:133]
	v_lshl_add_u64 v[2:3], s[46:47], 0, v[128:129]
	v_lshl_add_u64 v[0:1], s[44:45], 0, v[134:135]
	s_cselect_b64 s[8:9], -1, 0
	s_cmp_lg_u32 s24, 1
	v_lshl_add_u64 v[4:5], s[44:45], 0, v[130:131]
	s_cbranch_scc1 .LBB0_404
	s_barrier

.LBB0_435:
	s_cmp_eq_u32 s32, 1
	s_cbranch_scc0 .Lp2_tail
	v_writelane_b32 v241, s24, 2
	v_writelane_b32 v241, s25, 3
	v_writelane_b32 v241, s37, 4
	v_writelane_b32 v241, s38, 5
	v_writelane_b32 v241, s39, 6
	v_writelane_b32 v241, s40, 7
	v_writelane_b32 v241, s41, 8
	v_writelane_b32 v241, s42, 9
	v_writelane_b32 v241, s43, 10
	v_writelane_b32 v241, s44, 11
	v_writelane_b32 v241, s45, 12
	v_writelane_b32 v241, s46, 13
	v_writelane_b32 v241, s47, 14
	v_writelane_b32 v241, s48, 15
	v_writelane_b32 v241, s49, 16
	v_writelane_b32 v241, s50, 17
	v_writelane_b32 v241, s51, 18
	s_mov_b32 s32, 2
	v_readlane_b32 s24, v241, 0
	v_readlane_b32 s25, v241, 1
	s_branch .Lp2_A_entry
.Lp2_restoreB:
	v_readlane_b32 s24, v241, 2
	v_readlane_b32 s25, v241, 3
	v_readlane_b32 s37, v241, 4
	v_readlane_b32 s38, v241, 5
	v_readlane_b32 s39, v241, 6
	v_readlane_b32 s40, v241, 7
	v_readlane_b32 s41, v241, 8
	v_readlane_b32 s42, v241, 9
	v_readlane_b32 s43, v241, 10
	v_readlane_b32 s44, v241, 11
	v_readlane_b32 s45, v241, 12
	v_readlane_b32 s46, v241, 13
	v_readlane_b32 s47, v241, 14
	v_readlane_b32 s48, v241, 15
	v_readlane_b32 s49, v241, 16
	v_readlane_b32 s50, v241, 17
	v_readlane_b32 s51, v241, 18
